# GEMM pipeline fill: second-buffer stage loads issued before the first counted wait and barrier (all 8 GEMM call sites)
# speedup vs baseline: 1.0121x; 1.0010x over previous
.LBB0_338:
	s_mov_b64 s[6:7], 0x80
	v_lshl_add_u64 v[4:5], v[4:5], 0, s[6:7]
	s_add_i32 m0, s23, 0x18000
	s_nop 0
	global_load_lds_dwordx4 v[4:5], off
	v_lshl_add_u64 v[2:3], v[2:3], 0, s[6:7]
	s_add_i32 m0, s23, 0x1a000
	s_add_i32 s36, s23, 0x8000
	s_add_i32 s37, s23, 0xa000
	global_load_lds_dwordx4 v[2:3], off
	v_lshl_add_u64 v[0:1], v[0:1], 0, s[6:7]
	s_mov_b32 m0, s36
	s_add_u32 s0, s26, 0x40080
	global_load_lds_dwordx4 v[0:1], off
	v_lshl_add_u64 v[0:1], v[6:7], 0, s[6:7]
	s_mov_b32 m0, s37
	s_addc_u32 s1, s27, 0
	global_load_lds_dwordx4 v[0:1], off
	v_lshl_add_u64 v[0:1], s[0:1], 0, v[130:131]
	s_add_i32 m0, s23, 0x1c000
	v_and_b32_e32 v2, 48, v8
	global_load_lds_dwordx4 v[0:1], off
	v_lshl_add_u64 v[0:1], s[0:1], 0, v[134:135]
	s_add_i32 m0, s23, 0x1e000
	v_readlane_b32 s0, v254, 61
	global_load_lds_dwordx4 v[0:1], off
	s_waitcnt vmcnt(8)
	s_barrier
	v_and_b32_e32 v0, 15, v8
	v_or_b32_e32 v1, s0, v0
	v_lshlrev_b32_e32 v3, 6, v1
	s_movk_i32 s0, 0x3c0
	v_lshlrev_b32_e32 v1, 2, v1
	v_and_or_b32 v3, v3, s0, v2
	v_and_b32_e32 v1, 32, v1
	v_readlane_b32 s0, v254, 62
	v_lshl_or_b32 v0, v0, 6, v2
	v_lshlrev_b32_e32 v2, 2, v8
	v_bitop3_b32 v1, v3, s0, v1 bitop3:0xde
	v_and_b32_e32 v2, 32, v2
	v_readlane_b32 s0, v255, 1
	s_waitcnt vmcnt(6)
	s_add_i32 s38, 0, 0x10000
	s_add_i32 s39, 0, 0x14000
	v_bitop3_b32 v148, v0, s0, v2 bitop3:0xde
	v_lshlrev_b32_e32 v0, 14, v9
	v_and_b32_e32 v0, 0xffff8000, v0
	v_lshl_add_u32 v0, v10, 11, v0
	v_and_b32_e32 v2, 1, v9
	v_lshl_or_b32 v0, v2, 6, v0
	v_lshl_add_u32 v136, v11, 1, v0
	v_lshlrev_b32_e32 v0, 14, v12
	v_and_b32_e32 v0, 0xffff8000, v0
	v_lshl_add_u32 v0, v13, 11, v0
	v_and_b32_e32 v2, 1, v12
	v_lshl_or_b32 v0, v2, 6, v0
	v_mov_b32_e32 v137, v131
	v_lshl_add_u32 v138, v14, 1, v0
	v_mov_b32_e32 v139, v131
	v_mov_b64_e32 v[140:141], 0x480
	v_mov_b64_e32 v[142:143], 0x47f
	v_add_u32_e32 v149, s38, v148
	v_add_u32_e32 v150, s39, v148
	v_add_u32_e32 v151, 0, v1
	s_movk_i32 s40, 0x1200
	s_barrier
	s_branch .LBB0_341

.LBB0_514:
	s_sext_i32_i8 s51, s2
	v_and_b32_e32 v9, 15, v8
	v_readlane_b32 s2, v254, 61
	v_and_b32_e32 v11, 48, v8
	v_lshlrev_b32_e32 v8, 2, v8
	v_or_b32_e32 v10, s2, v9
	v_lshlrev_b32_e32 v12, 6, v10
	s_movk_i32 s2, 0x3c0
	v_lshlrev_b32_e32 v10, 2, v10
	v_and_or_b32 v12, v12, s2, v11
	v_and_b32_e32 v10, 32, v10
	v_readlane_b32 s2, v254, 62
	v_lshl_or_b32 v9, v9, 6, v11
	v_and_b32_e32 v8, 32, v8
	v_bitop3_b32 v10, v12, s2, v10 bitop3:0xde
	v_readlane_b32 s2, v255, 1
	s_add_i32 m0, s30, 0x18000
	v_bitop3_b32 v140, v9, s2, v8 bitop3:0xde
	s_mov_b64 s[2:3], 0x80
	v_lshl_add_u64 v[6:7], v[6:7], 0, s[2:3]
	global_load_lds_dwordx4 v[6:7], off
	v_lshl_add_u64 v[4:5], v[4:5], 0, s[2:3]
	s_add_i32 m0, s30, 0x1a000
	s_add_i32 s40, s30, 0x8000
	s_add_i32 s41, s30, 0xa000
	global_load_lds_dwordx4 v[4:5], off
	v_lshl_add_u64 v[2:3], v[2:3], 0, s[2:3]
	s_mov_b32 m0, s40
	s_add_u32 s4, s28, 0x18080
	global_load_lds_dwordx4 v[2:3], off
	v_lshl_add_u64 v[0:1], v[0:1], 0, s[2:3]
	s_mov_b32 m0, s41
	s_addc_u32 s5, s29, 0
	global_load_lds_dwordx4 v[0:1], off
	v_lshl_add_u64 v[0:1], s[4:5], 0, v[132:133]
	s_add_i32 m0, s30, 0x1c000
	v_readlane_b32 s6, v255, 6
	global_load_lds_dwordx4 v[0:1], off
	v_lshl_add_u64 v[0:1], s[4:5], 0, v[128:129]
	s_add_i32 m0, s30, 0x1e000
	s_add_u32 s4, s64, s90
	global_load_lds_dwordx4 v[0:1], off
	s_waitcnt vmcnt(8)
	s_barrier
	s_waitcnt vmcnt(6)
	v_readlane_b32 s5, v255, 7
	s_addc_u32 s5, s5, s6
	s_add_i32 s42, 0, 0x10000
	s_add_i32 s43, 0, 0x14000
	v_add_u32_e32 v141, 0, v10
	s_mov_b64 s[10:11], 0x180
	v_add_u32_e32 v142, s42, v140
	v_add_u32_e32 v143, s43, v140
	s_mov_b64 s[18:19], 0x100
	s_mov_b64 s[20:21], 0x200
	s_mov_b64 s[22:23], 0x280
	s_movk_i32 s44, 0xffa0
	s_movk_i32 s46, 0x1000
	s_movk_i32 s47, 0x7000
	s_add_i32 s48, s30, 0xc000
	s_barrier
	s_branch .LBB0_517

.LBB0_534:
	v_readlane_b32 s0, v255, 45
	s_cmp_gt_u32 s0, 1
	v_and_b32_e32 v9, 15, v8
	v_readlane_b32 s0, v254, 61
	v_and_b32_e32 v11, 48, v8
	s_mov_b64 s[4:5], 0x80
	v_or_b32_e32 v10, s0, v9
	v_lshlrev_b32_e32 v12, 6, v10
	s_movk_i32 s0, 0x3c0
	v_lshlrev_b32_e32 v10, 2, v10
	s_cselect_b64 s[2:3], -1, 0
	v_and_or_b32 v12, v12, s0, v11
	v_and_b32_e32 v10, 32, v10
	v_readlane_b32 s0, v254, 62
	v_lshlrev_b32_e32 v8, 2, v8
	v_lshl_add_u64 v[4:5], v[4:5], 0, s[4:5]
	s_add_i32 m0, s38, 0x18000
	v_bitop3_b32 v10, v12, s0, v10 bitop3:0xde
	v_lshl_or_b32 v9, v9, 6, v11
	v_and_b32_e32 v8, 32, v8
	v_readlane_b32 s0, v255, 46
	global_load_lds_dwordx4 v[4:5], off
	v_lshl_add_u64 v[2:3], v[2:3], 0, s[4:5]
	s_add_i32 m0, s38, 0x1a000
	s_add_i32 s42, s38, 0x8000
	s_add_i32 s43, s38, 0xa000
	v_bitop3_b32 v150, v9, s0, v8 bitop3:0xde
	global_load_lds_dwordx4 v[2:3], off
	v_lshl_add_u64 v[0:1], v[0:1], 0, s[4:5]
	s_mov_b32 m0, s42
	s_add_u32 s0, s34, 0x10080
	global_load_lds_dwordx4 v[0:1], off
	v_lshl_add_u64 v[0:1], v[6:7], 0, s[4:5]
	s_mov_b32 m0, s43
	s_addc_u32 s1, s35, 0
	global_load_lds_dwordx4 v[0:1], off
	v_lshl_add_u64 v[0:1], s[0:1], 0, v[130:131]
	s_add_i32 m0, s38, 0x1c000
	s_movk_i32 s20, 0xf000
	global_load_lds_dwordx4 v[0:1], off
	v_lshl_add_u64 v[0:1], s[0:1], 0, v[134:135]
	s_add_i32 m0, s38, 0x1e000
	s_add_u32 s10, s64, s90
	global_load_lds_dwordx4 v[0:1], off
	s_waitcnt vmcnt(8)
	s_barrier
	s_waitcnt vmcnt(6)
	v_readlane_b32 s0, v255, 7
	v_readlane_b32 s1, v255, 6
	s_addc_u32 s11, s0, s1
	s_add_i32 s44, 0, 0x10000
	s_add_i32 s45, 0, 0x14000
	v_add_u32_e32 v151, s44, v150
	v_add_u32_e32 v152, s45, v150
	v_add_u32_e32 v153, 0, v10
	s_mov_b64 s[14:15], 0x100
	s_mov_b64 s[18:19], 0x180
	s_mov_b32 s21, -1
	s_barrier
	s_branch .LBB0_537

.LBB0_919:
	s_mov_b64 s[6:7], 0x80
	v_lshl_add_u64 v[4:5], v[4:5], 0, s[6:7]
	s_add_i32 m0, s21, 0x18000
	s_nop 0
	global_load_lds_dwordx4 v[4:5], off
	v_lshl_add_u64 v[2:3], v[2:3], 0, s[6:7]
	s_add_i32 m0, s21, 0x1a000
	s_add_i32 s34, s21, 0x8000
	s_add_i32 s35, s21, 0xa000
	global_load_lds_dwordx4 v[2:3], off
	v_lshl_add_u64 v[0:1], v[0:1], 0, s[6:7]
	s_mov_b32 m0, s34
	s_add_u32 s8, s24, 0x40080
	global_load_lds_dwordx4 v[0:1], off
	v_lshl_add_u64 v[0:1], v[6:7], 0, s[6:7]
	s_mov_b32 m0, s35
	s_addc_u32 s9, s25, 0
	global_load_lds_dwordx4 v[0:1], off
	v_lshl_add_u64 v[0:1], s[8:9], 0, v[148:149]
	s_add_i32 m0, s21, 0x1c000
	s_sext_i32_i8 s38, s0
	global_load_lds_dwordx4 v[0:1], off
	v_lshl_add_u64 v[0:1], s[8:9], 0, v[144:145]
	s_add_i32 m0, s21, 0x1e000
	v_readlane_b32 s0, v254, 61
	global_load_lds_dwordx4 v[0:1], off
	s_waitcnt vmcnt(8)
	s_barrier
	v_and_b32_e32 v0, 15, v9
	v_or_b32_e32 v1, s0, v0
	v_and_b32_e32 v2, 48, v9
	v_lshlrev_b32_e32 v3, 6, v1
	s_movk_i32 s0, 0x3c0
	v_lshlrev_b32_e32 v1, 2, v1
	v_and_or_b32 v3, v3, s0, v2
	v_and_b32_e32 v1, 32, v1
	v_readlane_b32 s0, v254, 62
	v_lshl_or_b32 v0, v0, 6, v2
	v_lshlrev_b32_e32 v2, 2, v9
	v_bitop3_b32 v1, v3, s0, v1 bitop3:0xde
	v_and_b32_e32 v2, 32, v2
	v_readlane_b32 s0, v255, 1
	s_waitcnt vmcnt(6)
	s_add_i32 s36, 0, 0x10000
	s_add_i32 s37, 0, 0x14000
	v_bitop3_b32 v166, v0, s0, v2 bitop3:0xde
	v_lshlrev_b32_e32 v0, 14, v12
	v_and_b32_e32 v0, 0xffff8000, v0
	v_lshl_add_u32 v0, v13, 11, v0
	v_and_b32_e32 v2, 1, v12
	v_lshl_or_b32 v0, v2, 6, v0
	v_lshl_add_u32 v152, v14, 1, v0
	v_lshlrev_b32_e32 v0, 14, v8
	v_and_b32_e32 v0, 0xffff8000, v0
	v_lshl_add_u32 v0, v10, 11, v0
	v_and_b32_e32 v2, 1, v8
	v_lshl_or_b32 v0, v2, 6, v0
	v_mov_b32_e32 v153, v149
	v_lshl_add_u32 v154, v11, 1, v0
	v_mov_b32_e32 v155, v149
	v_mov_b64_e32 v[156:157], 0x200
	v_mov_b64_e32 v[158:159], 0x1ff
	v_add_u32_e32 v167, s36, v166
	v_add_u32_e32 v168, s37, v166
	v_add_u32_e32 v169, 0, v1
	s_mov_b64 s[8:9], 0xa0000
	s_mov_b64 s[10:11], 0xb0000
	s_barrier
	s_branch .LBB0_922

.LBB0_1003:
	s_add_u32 s12, s70, 0xa80000
	s_addc_u32 s13, s71, 0
	s_add_u32 s40, s70, 0x9c0200
	s_mov_b64 s[14:15], 0x80
	s_addc_u32 s41, s71, 0
	v_lshl_add_u64 v[4:5], v[4:5], 0, s[14:15]
	s_add_i32 m0, s36, 0x18000
	s_nop 0
	global_load_lds_dwordx4 v[4:5], off
	v_lshl_add_u64 v[2:3], v[2:3], 0, s[14:15]
	s_add_i32 m0, s36, 0x1a000
	s_add_i32 s42, s36, 0x8000
	s_add_i32 s43, s36, 0xa000
	global_load_lds_dwordx4 v[2:3], off
	v_lshl_add_u64 v[0:1], v[0:1], 0, s[14:15]
	s_mov_b32 m0, s42
	s_add_u32 s6, s28, 0x40080
	global_load_lds_dwordx4 v[0:1], off
	v_lshl_add_u64 v[0:1], v[6:7], 0, s[14:15]
	s_mov_b32 m0, s43
	s_addc_u32 s7, s29, 0
	global_load_lds_dwordx4 v[0:1], off
	v_lshl_add_u64 v[0:1], s[6:7], 0, v[178:179]
	s_add_i32 m0, s36, 0x1c000
	v_and_b32_e32 v2, 48, v8
	global_load_lds_dwordx4 v[0:1], off
	v_lshl_add_u64 v[0:1], s[6:7], 0, v[182:183]
	s_add_i32 m0, s36, 0x1e000
	v_readlane_b32 s7, v254, 61
	global_load_lds_dwordx4 v[0:1], off
	s_waitcnt vmcnt(8)
	s_barrier
	v_and_b32_e32 v0, 15, v8
	v_or_b32_e32 v1, s7, v0
	v_lshlrev_b32_e32 v3, 6, v1
	s_movk_i32 s6, 0x3c0
	v_lshlrev_b32_e32 v1, 2, v1
	v_and_or_b32 v3, v3, s6, v2
	v_and_b32_e32 v1, 32, v1
	v_readlane_b32 s6, v254, 62
	v_lshl_or_b32 v0, v0, 6, v2
	v_lshlrev_b32_e32 v2, 2, v8
	v_bitop3_b32 v1, v3, s6, v1 bitop3:0xde
	v_and_b32_e32 v2, 32, v2
	v_readlane_b32 s6, v255, 46
	s_cmp_lt_u32 s55, 64
	s_cselect_b64 s[16:17], -1, 0
	v_bitop3_b32 v219, v0, s6, v2 bitop3:0xde
	v_lshlrev_b32_e32 v0, 14, v9
	v_and_b32_e32 v0, 0xffff8000, v0
	v_lshl_add_u32 v0, v10, 11, v0
	v_and_b32_e32 v2, 1, v9
	v_lshl_or_b32 v0, v2, 6, v0
	v_lshl_add_u32 v184, v11, 1, v0
	v_lshlrev_b32_e32 v0, 14, v12
	v_readlane_b32 s6, v255, 45
	v_and_b32_e32 v0, 0xffff8000, v0
	s_lshl_b32 s6, s6, 2
	v_lshl_add_u32 v0, v13, 11, v0
	v_and_b32_e32 v2, 1, v12
	s_waitcnt vmcnt(6)
	s_add_i32 s44, s6, 0
	s_lshl_b32 s6, s7, 2
	v_lshl_or_b32 v0, v2, 6, v0
	s_add_i32 s45, s6, 0
	v_lshl_add_u32 v186, v14, 1, v0
	s_add_i32 s48, 0, 0x10000
	s_add_i32 s49, 0, 0x14000
	v_mbcnt_lo_u32_b32 v0, -1, 0
	s_add_i32 s44, s44, 0x20800
	s_add_i32 s45, s45, 0x21800
	v_mov_b32_e32 v185, v179
	v_mov_b32_e32 v187, v179
	v_mov_b64_e32 v[188:189], 0x200
	v_mov_b64_e32 v[190:191], 0x1ff
	v_add_u32_e32 v220, s48, v219
	v_add_u32_e32 v221, s49, v219
	v_add_u32_e32 v222, 0, v1
	v_mbcnt_hi_u32_b32 v223, -1, v0
	s_add_i32 s50, 0, 0x21c00
	v_mov_b32_e32 v224, 0x358637bd
	s_mov_b32 s10, s11
	s_barrier
	s_branch .LBB0_1006

.LBB0_1096:
	v_readlane_b32 s0, v255, 45
	s_lshl_b32 s29, s0, 4
	s_mov_b64 s[0:1], 0x80
	v_lshl_add_u64 v[4:5], v[4:5], 0, s[0:1]
	s_add_i32 m0, s17, 0x18000
	s_nop 0
	global_load_lds_dwordx4 v[4:5], off
	v_lshl_add_u64 v[2:3], v[2:3], 0, s[0:1]
	s_add_i32 m0, s17, 0x1a000
	s_add_i32 s30, s17, 0x8000
	s_add_i32 s31, s17, 0xa000
	global_load_lds_dwordx4 v[2:3], off
	v_lshl_add_u64 v[0:1], v[0:1], 0, s[0:1]
	s_mov_b32 m0, s30
	s_add_u32 s8, s20, 0x40080
	global_load_lds_dwordx4 v[0:1], off
	v_lshl_add_u64 v[0:1], v[6:7], 0, s[0:1]
	s_mov_b32 m0, s31
	s_addc_u32 s9, s21, 0
	global_load_lds_dwordx4 v[0:1], off
	v_lshl_add_u64 v[0:1], s[8:9], 0, v[132:133]
	s_add_i32 m0, s17, 0x1c000
	s_sext_i32_i16 s37, s6
	global_load_lds_dwordx4 v[0:1], off
	v_lshl_add_u64 v[0:1], s[8:9], 0, v[128:129]
	s_add_i32 m0, s17, 0x1e000
	v_readlane_b32 s6, v254, 61
	global_load_lds_dwordx4 v[0:1], off
	s_waitcnt vmcnt(8)
	s_barrier
	v_and_b32_e32 v0, 15, v9
	v_or_b32_e32 v1, s6, v0
	v_and_b32_e32 v2, 48, v9
	v_lshlrev_b32_e32 v3, 6, v1
	s_movk_i32 s6, 0x3c0
	v_lshlrev_b32_e32 v1, 2, v1
	v_and_or_b32 v3, v3, s6, v2
	v_and_b32_e32 v1, 32, v1
	v_readlane_b32 s6, v254, 62
	v_lshl_or_b32 v0, v0, 6, v2
	v_lshlrev_b32_e32 v2, 2, v9
	v_bitop3_b32 v1, v3, s6, v1 bitop3:0xde
	v_and_b32_e32 v2, 32, v2
	v_readlane_b32 s6, v255, 46
	s_waitcnt vmcnt(6)
	s_add_i32 s34, 0, 0x10000
	s_add_i32 s35, 0, 0x14000
	v_bitop3_b32 v144, v0, s6, v2 bitop3:0xde
	v_lshlrev_b32_e32 v0, 14, v12
	v_and_b32_e32 v0, 0xffff8000, v0
	v_lshl_add_u32 v0, v13, 11, v0
	v_and_b32_e32 v2, 1, v12
	v_lshl_or_b32 v0, v2, 6, v0
	v_lshl_add_u32 v136, v14, 1, v0
	v_lshlrev_b32_e32 v0, 14, v8
	v_and_b32_e32 v0, 0xffff8000, v0
	v_lshl_add_u32 v0, v10, 11, v0
	v_and_b32_e32 v2, 1, v8
	v_lshl_or_b32 v0, v2, 6, v0
	v_mov_b32_e32 v137, v133
	v_lshl_add_u32 v138, v11, 1, v0
	v_mov_b32_e32 v139, v133
	v_mov_b64_e32 v[140:141], 0xb00
	v_mov_b64_e32 v[142:143], 0xaff
	v_add_u32_e32 v145, s34, v144
	v_add_u32_e32 v146, s35, v144
	v_add_u32_e32 v147, 0, v1
	s_movk_i32 s36, 0x1600
	s_barrier
	s_branch .LBB0_1099

.LBB0_1170:
	s_mov_b64 s[8:9], 0x80
	v_lshl_add_u64 v[4:5], v[4:5], 0, s[8:9]
	s_add_i32 m0, s26, 0x18000
	s_nop 0
	global_load_lds_dwordx4 v[4:5], off
	v_lshl_add_u64 v[2:3], v[2:3], 0, s[8:9]
	s_add_i32 m0, s26, 0x1a000
	s_add_i32 s31, s26, 0x8000
	s_add_i32 s34, s26, 0xa000
	global_load_lds_dwordx4 v[2:3], off
	v_lshl_add_u64 v[0:1], v[0:1], 0, s[8:9]
	s_mov_b32 m0, s31
	s_add_u32 s6, s20, 0xb0080
	global_load_lds_dwordx4 v[0:1], off
	v_lshl_add_u64 v[0:1], v[6:7], 0, s[8:9]
	s_mov_b32 m0, s34
	s_addc_u32 s7, s21, 0
	global_load_lds_dwordx4 v[0:1], off
	v_lshl_add_u64 v[0:1], s[6:7], 0, v[146:147]
	s_add_i32 m0, s26, 0x1c000
	s_sext_i32_i8 s40, s1
	global_load_lds_dwordx4 v[0:1], off
	v_lshl_add_u64 v[0:1], s[6:7], 0, v[150:151]
	s_add_i32 m0, s26, 0x1e000
	v_readlane_b32 s1, v254, 61
	global_load_lds_dwordx4 v[0:1], off
	s_waitcnt vmcnt(8)
	s_barrier
	v_and_b32_e32 v0, 15, v8
	v_or_b32_e32 v1, s1, v0
	v_and_b32_e32 v2, 48, v8
	v_lshlrev_b32_e32 v3, 6, v1
	s_movk_i32 s1, 0x3c0
	v_lshlrev_b32_e32 v1, 2, v1
	v_and_or_b32 v3, v3, s1, v2
	v_and_b32_e32 v1, 32, v1
	v_readlane_b32 s1, v254, 62
	v_lshl_or_b32 v0, v0, 6, v2
	s_mov_b64 s[6:7], 0xb0080
	v_bitop3_b32 v3, v3, s1, v1 bitop3:0xde
	v_lshlrev_b32_e32 v1, 2, v8
	v_and_b32_e32 v1, 32, v1
	v_readlane_b32 s1, v255, 1
	s_waitcnt vmcnt(6)
	s_add_i32 s35, 0, 0x10000
	s_add_i32 s36, 0, 0x14000
	v_bitop3_b32 v166, v0, s1, v1 bitop3:0xde
	v_lshrrev_b32_e32 v1, 1, v9
	v_mul_lo_u32 v0, v11, s0
	s_mov_b32 s1, 0xb000
	v_mad_u64_u32 v[0:1], s[10:11], v1, s1, v[0:1]
	v_or_b32_e32 v0, v0, v10
	v_add_lshl_u32 v0, v0, v12, 1
	v_mov_b32_e32 v1, v147
	v_lshl_add_u64 v[152:153], v[0:1], 0, s[6:7]
	v_lshrrev_b32_e32 v1, 1, v13
	v_mul_lo_u32 v0, v14, s0
	v_mad_u64_u32 v[0:1], s[0:1], v1, s1, v[0:1]
	v_or_b32_e32 v0, v0, v15
	v_add_lshl_u32 v0, v0, v16, 1
	v_mov_b32_e32 v1, v147
	v_lshl_add_u64 v[154:155], v[0:1], 0, s[6:7]
	v_mov_b64_e32 v[156:157], 0x200
	v_mov_b64_e32 v[158:159], 0x1ff
	v_add_u32_e32 v167, s35, v166
	v_add_u32_e32 v168, s36, v166
	v_add_u32_e32 v169, 0, v3
	s_mov_b64 s[10:11], 0x80000
	s_mov_b64 s[12:13], 0x90000
	s_mov_b64 s[14:15], 0xa0000
	s_barrier
	s_branch .LBB0_1173

.LBB0_1257:
	s_add_u32 s12, s70, 0xa00000
	s_mov_b64 s[14:15], 0x80
	s_addc_u32 s13, s71, 0
	v_lshl_add_u64 v[4:5], v[4:5], 0, s[14:15]
	s_add_i32 m0, s38, 0x18000
	s_nop 0
	global_load_lds_dwordx4 v[4:5], off
	v_lshl_add_u64 v[2:3], v[2:3], 0, s[14:15]
	s_add_i32 m0, s38, 0x1a000
	s_add_i32 s42, s38, 0x8000
	s_add_i32 s43, s38, 0xa000
	global_load_lds_dwordx4 v[2:3], off
	v_lshl_add_u64 v[0:1], v[0:1], 0, s[14:15]
	s_mov_b32 m0, s42
	s_add_u32 s4, s34, 0xb0080
	global_load_lds_dwordx4 v[0:1], off
	v_lshl_add_u64 v[0:1], v[6:7], 0, s[14:15]
	s_mov_b32 m0, s43
	s_addc_u32 s5, s35, 0
	global_load_lds_dwordx4 v[0:1], off
	v_lshl_add_u64 v[0:1], s[4:5], 0, v[146:147]
	s_add_i32 m0, s38, 0x1c000
	v_readlane_b32 s8, v254, 61
	global_load_lds_dwordx4 v[0:1], off
	v_lshl_add_u64 v[0:1], s[4:5], 0, v[150:151]
	s_add_i32 m0, s38, 0x1e000
	v_and_b32_e32 v2, 48, v8
	global_load_lds_dwordx4 v[0:1], off
	s_waitcnt vmcnt(8)
	s_barrier
	v_and_b32_e32 v0, 15, v8
	v_or_b32_e32 v1, s8, v0
	v_lshlrev_b32_e32 v3, 6, v1
	s_movk_i32 s4, 0x3c0
	v_lshlrev_b32_e32 v1, 2, v1
	v_and_or_b32 v3, v3, s4, v2
	v_and_b32_e32 v1, 32, v1
	v_readlane_b32 s4, v254, 62
	s_cmp_lt_u32 s55, 64
	v_readlane_b32 s7, v255, 45
	v_bitop3_b32 v3, v3, s4, v1 bitop3:0xde
	v_lshlrev_b32_e32 v1, 2, v8
	s_cselect_b64 s[16:17], -1, 0
	s_lshl_b32 s7, s7, 2
	v_lshl_or_b32 v0, v0, 6, v2
	v_and_b32_e32 v1, 32, v1
	v_readlane_b32 s4, v255, 46
	s_add_i32 s46, s7, 0
	s_lshl_b32 s7, s8, 2
	v_bitop3_b32 v191, v0, s4, v1 bitop3:0xde
	s_add_i32 s47, s7, 0
	v_lshrrev_b32_e32 v1, 1, v9
	v_mul_lo_u32 v0, v11, s2
	s_mov_b32 s7, 0xb000
	v_mad_u64_u32 v[0:1], s[8:9], v1, s7, v[0:1]
	v_or_b32_e32 v0, v0, v10
	s_mov_b64 s[4:5], 0xb0080
	v_add_lshl_u32 v0, v0, v12, 1
	v_mov_b32_e32 v1, v147
	v_lshl_add_u64 v[152:153], v[0:1], 0, s[4:5]
	v_lshrrev_b32_e32 v1, 1, v13
	v_mul_lo_u32 v0, v14, s2
	v_mad_u64_u32 v[0:1], s[8:9], v1, s7, v[0:1]
	v_or_b32_e32 v0, v0, v15
	s_waitcnt vmcnt(6)
	v_add_lshl_u32 v0, v0, v16, 1
	v_mov_b32_e32 v1, v147
	v_lshl_add_u64 v[154:155], v[0:1], 0, s[4:5]
	s_add_i32 s48, 0, 0x10000
	s_add_i32 s49, 0, 0x14000
	v_mbcnt_lo_u32_b32 v0, -1, 0
	s_add_i32 s46, s46, 0x20800
	s_add_i32 s47, s47, 0x21800
	v_add_u32_e32 v192, s48, v191
	v_add_u32_e32 v193, s49, v191
	v_add_u32_e32 v194, 0, v3
	v_mbcnt_hi_u32_b32 v195, -1, v0
	s_mov_b64 s[18:19], 0x80000
	s_mov_b64 s[20:21], 0x90000
	s_mov_b64 s[22:23], 0xa0000
	s_add_i32 s50, 0, 0x21c00
	v_mov_b32_e32 v196, 0x358637bd
	s_mov_b32 s51, 0x800000
	s_mov_b32 s2, s3
	s_barrier
	s_branch .LBB0_1260
